# v13: + HGRN output S_prev staging loads batched, query-row loads in one round trip, far-field exp split so half of it runs under the first P.V MFMAs
# speedup vs baseline: 1.0306x; 1.0003x over previous
.LBB0_1582:
	s_and_b64 vcc, exec, s[40:41]
	s_cbranch_vccz .LBB0_1533
	s_nop 8
	v_add_f32_e32 v10, v229, v144
	v_add_f32_e32 v11, v229, v145
	v_exp_f32_e32 v10, v10
	v_exp_f32_e32 v11, v11
	v_cndmask_b32_e64 v160, 0, v10, s[4:5]
	v_cndmask_b32_e64 v161, 0, v11, s[4:5]
	v_add_f32_e32 v10, v229, v146
	v_add_f32_e32 v11, v229, v147
	v_exp_f32_e32 v10, v10
	v_exp_f32_e32 v11, v11
	v_cndmask_b32_e64 v162, 0, v10, s[4:5]
	v_cndmask_b32_e64 v163, 0, v11, s[4:5]
	v_add_f32_e32 v10, v229, v148
	v_add_f32_e32 v11, v229, v149
	v_exp_f32_e32 v10, v10
	v_exp_f32_e32 v11, v11
	v_cndmask_b32_e64 v164, 0, v10, s[4:5]
	v_cndmask_b32_e64 v165, 0, v11, s[4:5]
	v_add_f32_e32 v10, v229, v150
	v_add_f32_e32 v11, v229, v151
	v_exp_f32_e32 v10, v10
	v_exp_f32_e32 v11, v11
	v_cndmask_b32_e64 v166, 0, v10, s[4:5]
	v_cndmask_b32_e64 v167, 0, v11, s[4:5]
	v_add_f32_e32 v9, 0, v160
	v_add_f32_e32 v9, v161, v9
	v_add_f32_e32 v9, v162, v9
	v_add_f32_e32 v9, v163, v9
	v_add_f32_e32 v9, v164, v9
	v_add_f32_e32 v9, v165, v9
	v_add_f32_e32 v9, v166, v9
	v_add_f32_e32 v9, v167, v9
	v_cvt_pk_bf16_f32 v10, v160, v161
	v_cvt_pk_bf16_f32 v11, v162, v163
	v_cvt_pk_bf16_f32 v12, v164, v165
	v_cvt_pk_bf16_f32 v13, v166, v167
	s_waitcnt lgkmcnt(0)
	s_nop 0
	v_mfma_f32_32x32x16_bf16 v[16:31], v[10:13], v[240:243], v[16:31]
	v_mfma_f32_32x32x16_bf16 v[32:47], v[10:13], v[244:247], v[32:47]
	v_mfma_f32_32x32x16_bf16 v[96:111], v[10:13], v[248:251], v[96:111]
	v_mfma_f32_32x32x16_bf16 v[80:95], v[10:13], v[252:255], v[80:95]
	v_add_f32_e32 v14, v229, v152
	v_add_f32_e32 v15, v229, v153
	v_exp_f32_e32 v14, v14
	v_exp_f32_e32 v15, v15
	v_cndmask_b32_e64 v168, 0, v14, s[4:5]
	v_cndmask_b32_e64 v169, 0, v15, s[4:5]
	v_add_f32_e32 v14, v229, v154
	v_add_f32_e32 v15, v229, v155
	v_exp_f32_e32 v14, v14
	v_exp_f32_e32 v15, v15
	v_cndmask_b32_e64 v170, 0, v14, s[4:5]
	v_cndmask_b32_e64 v171, 0, v15, s[4:5]
	v_add_f32_e32 v14, v229, v156
	v_add_f32_e32 v15, v229, v157
	v_exp_f32_e32 v14, v14
	v_exp_f32_e32 v15, v15
	v_cndmask_b32_e64 v172, 0, v14, s[4:5]
	v_cndmask_b32_e64 v173, 0, v15, s[4:5]
	v_add_f32_e32 v14, v229, v158
	v_add_f32_e32 v15, v229, v159
	v_exp_f32_e32 v14, v14
	v_exp_f32_e32 v15, v15
	v_cndmask_b32_e64 v174, 0, v14, s[4:5]
	v_cndmask_b32_e64 v175, 0, v15, s[4:5]
	v_add_f32_e32 v9, v168, v9
	v_add_f32_e32 v9, v169, v9
	v_add_f32_e32 v9, v170, v9
	v_add_f32_e32 v9, v171, v9
	v_add_f32_e32 v9, v172, v9
	v_add_f32_e32 v9, v173, v9
	v_add_f32_e32 v9, v174, v9
	v_add_f32_e32 v9, v175, v9
	ds_read_b128 v[144:147], v8 offset:20480
	ds_read_b128 v[148:151], v8 offset:21504
	ds_read_b128 v[152:155], v8 offset:22528
	ds_read_b128 v[156:159], v8 offset:23552
	v_cvt_pk_bf16_f32 v10, v168, v169
	v_cvt_pk_bf16_f32 v11, v170, v171
	v_cvt_pk_bf16_f32 v12, v172, v173
	v_cvt_pk_bf16_f32 v13, v174, v175
	v_add_f32_e32 v1, v1, v9
	s_waitcnt lgkmcnt(3)
	s_nop 0
	v_mfma_f32_32x32x16_bf16 v[16:31], v[10:13], v[144:147], v[16:31]
	s_waitcnt lgkmcnt(2)
	v_mfma_f32_32x32x16_bf16 v[32:47], v[10:13], v[148:151], v[32:47]
	s_waitcnt lgkmcnt(1)
	v_mfma_f32_32x32x16_bf16 v[96:111], v[10:13], v[152:155], v[96:111]
	s_waitcnt lgkmcnt(0)
	v_mfma_f32_32x32x16_bf16 v[80:95], v[10:13], v[156:159], v[80:95]
	s_branch .LBB0_1534
